# decode attention: new-token V row fetched at unit start instead of in the last block
# speedup vs baseline: 1.0098x; 1.0019x over previous
.LBB0_306:
	v_add_lshl_u32 v182, s20, v12, 1
	global_load_dwordx2 v[180:181], v182, s[12:13] offset:2304
	s_lshl_b32 s22, s22, 10
	s_add_i32 s23, s22, 0
	s_add_i32 s23, s23, 0x20000
	s_ashr_i32 s9, s8, 31
	s_lshl_b64 s[16:17], s[16:17], 2
	v_lshl_add_u32 v22, v194, 2, s23
	s_add_u32 s16, s84, s16
	ds_write_b32 v22, v2
	s_nop 0
	s_addc_u32 s17, s85, s17
	s_waitcnt lgkmcnt(0)
	v_and_b32_e32 v148, 15, v194
	v_lshlrev_b32_e32 v150, 4, v148
	v_add_u32_e32 v151, s23, v150
	ds_read_b128 v[24:27], v151
	v_lshl_add_u32 v150, v195, 9, v150
	s_lshl_b32 s32, s20, 2
	v_lshl_add_u32 v149, v195, 2, v151
	v_add_u32_e32 v150, s32, v150
	s_lshl_b32 s32, s21, 2
	v_mov_b32_e32 v152, s32
	s_nop 3
	global_load_dword v29, v152, s[10:11]
	s_lshl_b64 s[14:15], s[14:15], 16
	v_mov_b32_e32 v146, 0
	v_mov_b32_e32 v147, 0
	global_load_dwordx4 v[78:81], v150, s[16:17]
	global_load_dwordx4 v[82:85], v150, s[16:17] offset:2048
	s_add_u32 s16, s16, 0x1000
	s_addc_u32 s17, s17, 0
	global_load_dwordx4 v[86:89], v150, s[16:17]
	global_load_dwordx4 v[90:93], v150, s[16:17] offset:2048
	s_add_u32 s16, s16, 0x1000
	s_addc_u32 s17, s17, 0
	global_load_dwordx4 v[94:97], v150, s[16:17]
	global_load_dwordx4 v[98:101], v150, s[16:17] offset:2048
	s_add_u32 s16, s16, 0x1000
	s_addc_u32 s17, s17, 0
	global_load_dwordx4 v[102:105], v150, s[16:17]
	global_load_dwordx4 v[106:109], v150, s[16:17] offset:2048
	s_add_u32 s16, s16, 0x1000
	s_addc_u32 s17, s17, 0
	global_load_dwordx4 v[110:113], v150, s[16:17]
	global_load_dwordx4 v[114:117], v150, s[16:17] offset:2048
	s_add_u32 s16, s16, 0x1000
	s_addc_u32 s17, s17, 0
	global_load_dwordx4 v[118:121], v150, s[16:17]
	global_load_dwordx4 v[122:125], v150, s[16:17] offset:2048
	s_add_u32 s16, s16, 0x1000
	s_addc_u32 s17, s17, 0
	global_load_dwordx4 v[126:129], v150, s[16:17]
	global_load_dwordx4 v[130:133], v150, s[16:17] offset:2048
	s_add_u32 s16, s16, 0x1000
	s_addc_u32 s17, s17, 0
	global_load_dwordx4 v[134:137], v150, s[16:17]
	global_load_dwordx4 v[138:141], v150, s[16:17] offset:2048
	s_add_u32 s16, s16, 0x1000
	s_addc_u32 s17, s17, 0
	s_waitcnt lgkmcnt(0)
	s_waitcnt vmcnt(15)
	v_mul_f32_e32 v142, v24, v78
	v_fmac_f32_e32 v142, v25, v79
	v_fmac_f32_e32 v142, v26, v80
	v_fmac_f32_e32 v142, v27, v81
	global_load_dwordx4 v[78:81], v150, s[16:17]
	s_waitcnt vmcnt(15)
	v_mul_f32_e32 v143, v24, v82
	v_fmac_f32_e32 v143, v25, v83
	v_fmac_f32_e32 v143, v26, v84
	v_fmac_f32_e32 v143, v27, v85
	global_load_dwordx4 v[82:85], v150, s[16:17] offset:2048
	s_add_u32 s16, s16, 0x1000
	s_addc_u32 s17, s17, 0
	s_waitcnt vmcnt(15)
	v_mul_f32_e32 v144, v24, v86
	v_fmac_f32_e32 v144, v25, v87
	v_fmac_f32_e32 v144, v26, v88
	v_fmac_f32_e32 v144, v27, v89
	global_load_dwordx4 v[86:89], v150, s[16:17]
	s_waitcnt vmcnt(15)
	v_mul_f32_e32 v145, v24, v90
	v_fmac_f32_e32 v145, v25, v91
	v_fmac_f32_e32 v145, v26, v92
	v_fmac_f32_e32 v145, v27, v93
	global_load_dwordx4 v[90:93], v150, s[16:17] offset:2048
	s_add_u32 s16, s16, 0x1000
	s_addc_u32 s17, s17, 0
	v_add_f32_dpp v142, v142, v142 quad_perm:[1,0,3,2] row_mask:0xf bank_mask:0xf
	v_add_f32_dpp v143, v143, v143 quad_perm:[1,0,3,2] row_mask:0xf bank_mask:0xf
	v_add_f32_dpp v144, v144, v144 quad_perm:[1,0,3,2] row_mask:0xf bank_mask:0xf
	v_add_f32_dpp v145, v145, v145 quad_perm:[1,0,3,2] row_mask:0xf bank_mask:0xf
	v_add_f32_dpp v142, v142, v142 quad_perm:[2,3,0,1] row_mask:0xf bank_mask:0xf
	v_add_f32_dpp v143, v143, v143 quad_perm:[2,3,0,1] row_mask:0xf bank_mask:0xf
	v_add_f32_dpp v144, v144, v144 quad_perm:[2,3,0,1] row_mask:0xf bank_mask:0xf
	v_add_f32_dpp v145, v145, v145 quad_perm:[2,3,0,1] row_mask:0xf bank_mask:0xf
	v_add_f32_dpp v142, v142, v142 row_half_mirror row_mask:0xf bank_mask:0xf
	v_add_f32_dpp v143, v143, v143 row_half_mirror row_mask:0xf bank_mask:0xf
	v_add_f32_dpp v144, v144, v144 row_half_mirror row_mask:0xf bank_mask:0xf
	v_add_f32_dpp v145, v145, v145 row_half_mirror row_mask:0xf bank_mask:0xf
	v_add_f32_dpp v142, v142, v142 row_mirror row_mask:0xf bank_mask:0xf
	v_add_f32_dpp v143, v143, v143 row_mirror row_mask:0xf bank_mask:0xf
	v_add_f32_dpp v144, v144, v144 row_mirror row_mask:0xf bank_mask:0xf
	v_add_f32_dpp v145, v145, v145 row_mirror row_mask:0xf bank_mask:0xf
	s_nop 1
	v_cmp_eq_u32_e32 vcc, 0, v148
	v_cndmask_b32_e32 v146, v146, v142, vcc
	v_cmp_eq_u32_e32 vcc, 1, v148
	v_cndmask_b32_e32 v146, v146, v143, vcc
	v_cmp_eq_u32_e32 vcc, 2, v148
	v_cndmask_b32_e32 v146, v146, v144, vcc
	v_cmp_eq_u32_e32 vcc, 3, v148
	v_cndmask_b32_e32 v146, v146, v145, vcc
	s_waitcnt vmcnt(15)
	v_mul_f32_e32 v142, v24, v94
	v_fmac_f32_e32 v142, v25, v95
	v_fmac_f32_e32 v142, v26, v96
	v_fmac_f32_e32 v142, v27, v97
	global_load_dwordx4 v[94:97], v150, s[16:17]
	s_waitcnt vmcnt(15)
	v_mul_f32_e32 v143, v24, v98
	v_fmac_f32_e32 v143, v25, v99
	v_fmac_f32_e32 v143, v26, v100
	v_fmac_f32_e32 v143, v27, v101
	global_load_dwordx4 v[98:101], v150, s[16:17] offset:2048
	s_add_u32 s16, s16, 0x1000
	s_addc_u32 s17, s17, 0
	s_waitcnt vmcnt(15)
	v_mul_f32_e32 v144, v24, v102
	v_fmac_f32_e32 v144, v25, v103
	v_fmac_f32_e32 v144, v26, v104
	v_fmac_f32_e32 v144, v27, v105
	global_load_dwordx4 v[102:105], v150, s[16:17]
	s_waitcnt vmcnt(15)
	v_mul_f32_e32 v145, v24, v106
	v_fmac_f32_e32 v145, v25, v107
	v_fmac_f32_e32 v145, v26, v108
	v_fmac_f32_e32 v145, v27, v109
	global_load_dwordx4 v[106:109], v150, s[16:17] offset:2048
	s_add_u32 s16, s16, 0x1000
	s_addc_u32 s17, s17, 0
	v_add_f32_dpp v142, v142, v142 quad_perm:[1,0,3,2] row_mask:0xf bank_mask:0xf
	v_add_f32_dpp v143, v143, v143 quad_perm:[1,0,3,2] row_mask:0xf bank_mask:0xf
	v_add_f32_dpp v144, v144, v144 quad_perm:[1,0,3,2] row_mask:0xf bank_mask:0xf
	v_add_f32_dpp v145, v145, v145 quad_perm:[1,0,3,2] row_mask:0xf bank_mask:0xf
	v_add_f32_dpp v142, v142, v142 quad_perm:[2,3,0,1] row_mask:0xf bank_mask:0xf
	v_add_f32_dpp v143, v143, v143 quad_perm:[2,3,0,1] row_mask:0xf bank_mask:0xf
	v_add_f32_dpp v144, v144, v144 quad_perm:[2,3,0,1] row_mask:0xf bank_mask:0xf
	v_add_f32_dpp v145, v145, v145 quad_perm:[2,3,0,1] row_mask:0xf bank_mask:0xf
	v_add_f32_dpp v142, v142, v142 row_half_mirror row_mask:0xf bank_mask:0xf
	v_add_f32_dpp v143, v143, v143 row_half_mirror row_mask:0xf bank_mask:0xf
	v_add_f32_dpp v144, v144, v144 row_half_mirror row_mask:0xf bank_mask:0xf
	v_add_f32_dpp v145, v145, v145 row_half_mirror row_mask:0xf bank_mask:0xf
	v_add_f32_dpp v142, v142, v142 row_mirror row_mask:0xf bank_mask:0xf
	v_add_f32_dpp v143, v143, v143 row_mirror row_mask:0xf bank_mask:0xf
	v_add_f32_dpp v144, v144, v144 row_mirror row_mask:0xf bank_mask:0xf
	v_add_f32_dpp v145, v145, v145 row_mirror row_mask:0xf bank_mask:0xf
	s_nop 1
	v_cmp_eq_u32_e32 vcc, 4, v148
	v_cndmask_b32_e32 v146, v146, v142, vcc
	v_cmp_eq_u32_e32 vcc, 5, v148
	v_cndmask_b32_e32 v146, v146, v143, vcc
	v_cmp_eq_u32_e32 vcc, 6, v148
	v_cndmask_b32_e32 v146, v146, v144, vcc
	v_cmp_eq_u32_e32 vcc, 7, v148
	v_cndmask_b32_e32 v146, v146, v145, vcc
	s_waitcnt vmcnt(15)
	v_mul_f32_e32 v142, v24, v110
	v_fmac_f32_e32 v142, v25, v111
	v_fmac_f32_e32 v142, v26, v112
	v_fmac_f32_e32 v142, v27, v113
	global_load_dwordx4 v[110:113], v150, s[16:17]
	s_waitcnt vmcnt(15)
	v_mul_f32_e32 v143, v24, v114
	v_fmac_f32_e32 v143, v25, v115
	v_fmac_f32_e32 v143, v26, v116
	v_fmac_f32_e32 v143, v27, v117
	global_load_dwordx4 v[114:117], v150, s[16:17] offset:2048
	s_add_u32 s16, s16, 0x1000
	s_addc_u32 s17, s17, 0
	s_waitcnt vmcnt(15)
	v_mul_f32_e32 v144, v24, v118
	v_fmac_f32_e32 v144, v25, v119
	v_fmac_f32_e32 v144, v26, v120
	v_fmac_f32_e32 v144, v27, v121
	global_load_dwordx4 v[118:121], v150, s[16:17]
	s_waitcnt vmcnt(15)
	v_mul_f32_e32 v145, v24, v122
	v_fmac_f32_e32 v145, v25, v123
	v_fmac_f32_e32 v145, v26, v124
	v_fmac_f32_e32 v145, v27, v125
	global_load_dwordx4 v[122:125], v150, s[16:17] offset:2048
	s_add_u32 s16, s16, 0x1000
	s_addc_u32 s17, s17, 0
	v_add_f32_dpp v142, v142, v142 quad_perm:[1,0,3,2] row_mask:0xf bank_mask:0xf
	v_add_f32_dpp v143, v143, v143 quad_perm:[1,0,3,2] row_mask:0xf bank_mask:0xf
	v_add_f32_dpp v144, v144, v144 quad_perm:[1,0,3,2] row_mask:0xf bank_mask:0xf
	v_add_f32_dpp v145, v145, v145 quad_perm:[1,0,3,2] row_mask:0xf bank_mask:0xf
	v_add_f32_dpp v142, v142, v142 quad_perm:[2,3,0,1] row_mask:0xf bank_mask:0xf
	v_add_f32_dpp v143, v143, v143 quad_perm:[2,3,0,1] row_mask:0xf bank_mask:0xf
	v_add_f32_dpp v144, v144, v144 quad_perm:[2,3,0,1] row_mask:0xf bank_mask:0xf
	v_add_f32_dpp v145, v145, v145 quad_perm:[2,3,0,1] row_mask:0xf bank_mask:0xf
	v_add_f32_dpp v142, v142, v142 row_half_mirror row_mask:0xf bank_mask:0xf
	v_add_f32_dpp v143, v143, v143 row_half_mirror row_mask:0xf bank_mask:0xf
	v_add_f32_dpp v144, v144, v144 row_half_mirror row_mask:0xf bank_mask:0xf
	v_add_f32_dpp v145, v145, v145 row_half_mirror row_mask:0xf bank_mask:0xf
	v_add_f32_dpp v142, v142, v142 row_mirror row_mask:0xf bank_mask:0xf
	v_add_f32_dpp v143, v143, v143 row_mirror row_mask:0xf bank_mask:0xf
	v_add_f32_dpp v144, v144, v144 row_mirror row_mask:0xf bank_mask:0xf
	v_add_f32_dpp v145, v145, v145 row_mirror row_mask:0xf bank_mask:0xf
	s_nop 1
	v_cmp_eq_u32_e32 vcc, 8, v148
	v_cndmask_b32_e32 v146, v146, v142, vcc
	v_cmp_eq_u32_e32 vcc, 9, v148
	v_cndmask_b32_e32 v146, v146, v143, vcc
	v_cmp_eq_u32_e32 vcc, 10, v148
	v_cndmask_b32_e32 v146, v146, v144, vcc
	v_cmp_eq_u32_e32 vcc, 11, v148
	v_cndmask_b32_e32 v146, v146, v145, vcc
	s_waitcnt vmcnt(15)
	v_mul_f32_e32 v142, v24, v126
	v_fmac_f32_e32 v142, v25, v127
	v_fmac_f32_e32 v142, v26, v128
	v_fmac_f32_e32 v142, v27, v129
	global_load_dwordx4 v[126:129], v150, s[16:17]
	s_waitcnt vmcnt(15)
	v_mul_f32_e32 v143, v24, v130
	v_fmac_f32_e32 v143, v25, v131
	v_fmac_f32_e32 v143, v26, v132
	v_fmac_f32_e32 v143, v27, v133
	global_load_dwordx4 v[130:133], v150, s[16:17] offset:2048
	s_add_u32 s16, s16, 0x1000
	s_addc_u32 s17, s17, 0
	s_waitcnt vmcnt(15)
	v_mul_f32_e32 v144, v24, v134
	v_fmac_f32_e32 v144, v25, v135
	v_fmac_f32_e32 v144, v26, v136
	v_fmac_f32_e32 v144, v27, v137
	global_load_dwordx4 v[134:137], v150, s[16:17]
	s_waitcnt vmcnt(15)
	v_mul_f32_e32 v145, v24, v138
	v_fmac_f32_e32 v145, v25, v139
	v_fmac_f32_e32 v145, v26, v140
	v_fmac_f32_e32 v145, v27, v141
	global_load_dwordx4 v[138:141], v150, s[16:17] offset:2048
	s_add_u32 s16, s16, 0x1000
	s_addc_u32 s17, s17, 0
	v_add_f32_dpp v142, v142, v142 quad_perm:[1,0,3,2] row_mask:0xf bank_mask:0xf
	v_add_f32_dpp v143, v143, v143 quad_perm:[1,0,3,2] row_mask:0xf bank_mask:0xf
	v_add_f32_dpp v144, v144, v144 quad_perm:[1,0,3,2] row_mask:0xf bank_mask:0xf
	v_add_f32_dpp v145, v145, v145 quad_perm:[1,0,3,2] row_mask:0xf bank_mask:0xf
	v_add_f32_dpp v142, v142, v142 quad_perm:[2,3,0,1] row_mask:0xf bank_mask:0xf
	v_add_f32_dpp v143, v143, v143 quad_perm:[2,3,0,1] row_mask:0xf bank_mask:0xf
	v_add_f32_dpp v144, v144, v144 quad_perm:[2,3,0,1] row_mask:0xf bank_mask:0xf
	v_add_f32_dpp v145, v145, v145 quad_perm:[2,3,0,1] row_mask:0xf bank_mask:0xf
	v_add_f32_dpp v142, v142, v142 row_half_mirror row_mask:0xf bank_mask:0xf
	v_add_f32_dpp v143, v143, v143 row_half_mirror row_mask:0xf bank_mask:0xf
	v_add_f32_dpp v144, v144, v144 row_half_mirror row_mask:0xf bank_mask:0xf
	v_add_f32_dpp v145, v145, v145 row_half_mirror row_mask:0xf bank_mask:0xf
	v_add_f32_dpp v142, v142, v142 row_mirror row_mask:0xf bank_mask:0xf
	v_add_f32_dpp v143, v143, v143 row_mirror row_mask:0xf bank_mask:0xf
	v_add_f32_dpp v144, v144, v144 row_mirror row_mask:0xf bank_mask:0xf
	v_add_f32_dpp v145, v145, v145 row_mirror row_mask:0xf bank_mask:0xf
	s_nop 1
	v_cmp_eq_u32_e32 vcc, 12, v148
	v_cndmask_b32_e32 v146, v146, v142, vcc
	v_cmp_eq_u32_e32 vcc, 13, v148
	v_cndmask_b32_e32 v146, v146, v143, vcc
	v_cmp_eq_u32_e32 vcc, 14, v148
	v_cndmask_b32_e32 v146, v146, v144, vcc
	v_cmp_eq_u32_e32 vcc, 15, v148
	v_cndmask_b32_e32 v146, v146, v145, vcc
	s_waitcnt vmcnt(15)
	v_mul_f32_e32 v142, v24, v78
	v_fmac_f32_e32 v142, v25, v79
	v_fmac_f32_e32 v142, v26, v80
	v_fmac_f32_e32 v142, v27, v81
	s_waitcnt vmcnt(14)
	v_mul_f32_e32 v143, v24, v82
	v_fmac_f32_e32 v143, v25, v83
	v_fmac_f32_e32 v143, v26, v84
	v_fmac_f32_e32 v143, v27, v85
	s_waitcnt vmcnt(13)
	v_mul_f32_e32 v144, v24, v86
	v_fmac_f32_e32 v144, v25, v87
	v_fmac_f32_e32 v144, v26, v88
	v_fmac_f32_e32 v144, v27, v89
	s_waitcnt vmcnt(12)
	v_mul_f32_e32 v145, v24, v90
	v_fmac_f32_e32 v145, v25, v91
	v_fmac_f32_e32 v145, v26, v92
	v_fmac_f32_e32 v145, v27, v93
	v_add_f32_dpp v142, v142, v142 quad_perm:[1,0,3,2] row_mask:0xf bank_mask:0xf
	v_add_f32_dpp v143, v143, v143 quad_perm:[1,0,3,2] row_mask:0xf bank_mask:0xf
	v_add_f32_dpp v144, v144, v144 quad_perm:[1,0,3,2] row_mask:0xf bank_mask:0xf
	v_add_f32_dpp v145, v145, v145 quad_perm:[1,0,3,2] row_mask:0xf bank_mask:0xf
	v_add_f32_dpp v142, v142, v142 quad_perm:[2,3,0,1] row_mask:0xf bank_mask:0xf
	v_add_f32_dpp v143, v143, v143 quad_perm:[2,3,0,1] row_mask:0xf bank_mask:0xf
	v_add_f32_dpp v144, v144, v144 quad_perm:[2,3,0,1] row_mask:0xf bank_mask:0xf
	v_add_f32_dpp v145, v145, v145 quad_perm:[2,3,0,1] row_mask:0xf bank_mask:0xf
	v_add_f32_dpp v142, v142, v142 row_half_mirror row_mask:0xf bank_mask:0xf
	v_add_f32_dpp v143, v143, v143 row_half_mirror row_mask:0xf bank_mask:0xf
	v_add_f32_dpp v144, v144, v144 row_half_mirror row_mask:0xf bank_mask:0xf
	v_add_f32_dpp v145, v145, v145 row_half_mirror row_mask:0xf bank_mask:0xf
	v_add_f32_dpp v142, v142, v142 row_mirror row_mask:0xf bank_mask:0xf
	v_add_f32_dpp v143, v143, v143 row_mirror row_mask:0xf bank_mask:0xf
	v_add_f32_dpp v144, v144, v144 row_mirror row_mask:0xf bank_mask:0xf
	v_add_f32_dpp v145, v145, v145 row_mirror row_mask:0xf bank_mask:0xf
	s_nop 1
	v_cmp_eq_u32_e32 vcc, 0, v148
	v_cndmask_b32_e32 v147, v147, v142, vcc
	v_cmp_eq_u32_e32 vcc, 1, v148
	v_cndmask_b32_e32 v147, v147, v143, vcc
	v_cmp_eq_u32_e32 vcc, 2, v148
	v_cndmask_b32_e32 v147, v147, v144, vcc
	v_cmp_eq_u32_e32 vcc, 3, v148
	v_cndmask_b32_e32 v147, v147, v145, vcc
	s_waitcnt vmcnt(11)
	v_mul_f32_e32 v142, v24, v94
	v_fmac_f32_e32 v142, v25, v95
	v_fmac_f32_e32 v142, v26, v96
	v_fmac_f32_e32 v142, v27, v97
	s_waitcnt vmcnt(10)
	v_mul_f32_e32 v143, v24, v98
	v_fmac_f32_e32 v143, v25, v99
	v_fmac_f32_e32 v143, v26, v100
	v_fmac_f32_e32 v143, v27, v101
	s_waitcnt vmcnt(9)
	v_mul_f32_e32 v144, v24, v102
	v_fmac_f32_e32 v144, v25, v103
	v_fmac_f32_e32 v144, v26, v104
	v_fmac_f32_e32 v144, v27, v105
	s_waitcnt vmcnt(8)
	v_mul_f32_e32 v145, v24, v106
	v_fmac_f32_e32 v145, v25, v107
	v_fmac_f32_e32 v145, v26, v108
	v_fmac_f32_e32 v145, v27, v109
	v_add_f32_dpp v142, v142, v142 quad_perm:[1,0,3,2] row_mask:0xf bank_mask:0xf
	v_add_f32_dpp v143, v143, v143 quad_perm:[1,0,3,2] row_mask:0xf bank_mask:0xf
	v_add_f32_dpp v144, v144, v144 quad_perm:[1,0,3,2] row_mask:0xf bank_mask:0xf
	v_add_f32_dpp v145, v145, v145 quad_perm:[1,0,3,2] row_mask:0xf bank_mask:0xf
	v_add_f32_dpp v142, v142, v142 quad_perm:[2,3,0,1] row_mask:0xf bank_mask:0xf
	v_add_f32_dpp v143, v143, v143 quad_perm:[2,3,0,1] row_mask:0xf bank_mask:0xf
	v_add_f32_dpp v144, v144, v144 quad_perm:[2,3,0,1] row_mask:0xf bank_mask:0xf
	v_add_f32_dpp v145, v145, v145 quad_perm:[2,3,0,1] row_mask:0xf bank_mask:0xf
	v_add_f32_dpp v142, v142, v142 row_half_mirror row_mask:0xf bank_mask:0xf
	v_add_f32_dpp v143, v143, v143 row_half_mirror row_mask:0xf bank_mask:0xf
	v_add_f32_dpp v144, v144, v144 row_half_mirror row_mask:0xf bank_mask:0xf
	v_add_f32_dpp v145, v145, v145 row_half_mirror row_mask:0xf bank_mask:0xf
	v_add_f32_dpp v142, v142, v142 row_mirror row_mask:0xf bank_mask:0xf
	v_add_f32_dpp v143, v143, v143 row_mirror row_mask:0xf bank_mask:0xf
	v_add_f32_dpp v144, v144, v144 row_mirror row_mask:0xf bank_mask:0xf
	v_add_f32_dpp v145, v145, v145 row_mirror row_mask:0xf bank_mask:0xf
	s_nop 1
	v_cmp_eq_u32_e32 vcc, 4, v148
	v_cndmask_b32_e32 v147, v147, v142, vcc
	v_cmp_eq_u32_e32 vcc, 5, v148
	v_cndmask_b32_e32 v147, v147, v143, vcc
	v_cmp_eq_u32_e32 vcc, 6, v148
	v_cndmask_b32_e32 v147, v147, v144, vcc
	v_cmp_eq_u32_e32 vcc, 7, v148
	v_cndmask_b32_e32 v147, v147, v145, vcc
	s_waitcnt vmcnt(7)
	v_mul_f32_e32 v142, v24, v110
	v_fmac_f32_e32 v142, v25, v111
	v_fmac_f32_e32 v142, v26, v112
	v_fmac_f32_e32 v142, v27, v113
	s_waitcnt vmcnt(6)
	v_mul_f32_e32 v143, v24, v114
	v_fmac_f32_e32 v143, v25, v115
	v_fmac_f32_e32 v143, v26, v116
	v_fmac_f32_e32 v143, v27, v117
	s_waitcnt vmcnt(5)
	v_mul_f32_e32 v144, v24, v118
	v_fmac_f32_e32 v144, v25, v119
	v_fmac_f32_e32 v144, v26, v120
	v_fmac_f32_e32 v144, v27, v121
	s_waitcnt vmcnt(4)
	v_mul_f32_e32 v145, v24, v122
	v_fmac_f32_e32 v145, v25, v123
	v_fmac_f32_e32 v145, v26, v124
	v_fmac_f32_e32 v145, v27, v125
	v_add_f32_dpp v142, v142, v142 quad_perm:[1,0,3,2] row_mask:0xf bank_mask:0xf
	v_add_f32_dpp v143, v143, v143 quad_perm:[1,0,3,2] row_mask:0xf bank_mask:0xf
	v_add_f32_dpp v144, v144, v144 quad_perm:[1,0,3,2] row_mask:0xf bank_mask:0xf
	v_add_f32_dpp v145, v145, v145 quad_perm:[1,0,3,2] row_mask:0xf bank_mask:0xf
	v_add_f32_dpp v142, v142, v142 quad_perm:[2,3,0,1] row_mask:0xf bank_mask:0xf
	v_add_f32_dpp v143, v143, v143 quad_perm:[2,3,0,1] row_mask:0xf bank_mask:0xf
	v_add_f32_dpp v144, v144, v144 quad_perm:[2,3,0,1] row_mask:0xf bank_mask:0xf
	v_add_f32_dpp v145, v145, v145 quad_perm:[2,3,0,1] row_mask:0xf bank_mask:0xf
	v_add_f32_dpp v142, v142, v142 row_half_mirror row_mask:0xf bank_mask:0xf
	v_add_f32_dpp v143, v143, v143 row_half_mirror row_mask:0xf bank_mask:0xf
	v_add_f32_dpp v144, v144, v144 row_half_mirror row_mask:0xf bank_mask:0xf
	v_add_f32_dpp v145, v145, v145 row_half_mirror row_mask:0xf bank_mask:0xf
	v_add_f32_dpp v142, v142, v142 row_mirror row_mask:0xf bank_mask:0xf
	v_add_f32_dpp v143, v143, v143 row_mirror row_mask:0xf bank_mask:0xf
	v_add_f32_dpp v144, v144, v144 row_mirror row_mask:0xf bank_mask:0xf
	v_add_f32_dpp v145, v145, v145 row_mirror row_mask:0xf bank_mask:0xf
	s_nop 1
	v_cmp_eq_u32_e32 vcc, 8, v148
	v_cndmask_b32_e32 v147, v147, v142, vcc
	v_cmp_eq_u32_e32 vcc, 9, v148
	v_cndmask_b32_e32 v147, v147, v143, vcc
	v_cmp_eq_u32_e32 vcc, 10, v148
	v_cndmask_b32_e32 v147, v147, v144, vcc
	v_cmp_eq_u32_e32 vcc, 11, v148
	v_cndmask_b32_e32 v147, v147, v145, vcc
	s_waitcnt vmcnt(3)
	v_mul_f32_e32 v142, v24, v126
	v_fmac_f32_e32 v142, v25, v127
	v_fmac_f32_e32 v142, v26, v128
	v_fmac_f32_e32 v142, v27, v129
	s_waitcnt vmcnt(2)
	v_mul_f32_e32 v143, v24, v130
	v_fmac_f32_e32 v143, v25, v131
	v_fmac_f32_e32 v143, v26, v132
	v_fmac_f32_e32 v143, v27, v133
	s_waitcnt vmcnt(1)
	v_mul_f32_e32 v144, v24, v134
	v_fmac_f32_e32 v144, v25, v135
	v_fmac_f32_e32 v144, v26, v136
	v_fmac_f32_e32 v144, v27, v137
	s_waitcnt vmcnt(0)
	v_mul_f32_e32 v145, v24, v138
	v_fmac_f32_e32 v145, v25, v139
	v_fmac_f32_e32 v145, v26, v140
	v_fmac_f32_e32 v145, v27, v141
	v_add_f32_dpp v142, v142, v142 quad_perm:[1,0,3,2] row_mask:0xf bank_mask:0xf
	v_add_f32_dpp v143, v143, v143 quad_perm:[1,0,3,2] row_mask:0xf bank_mask:0xf
	v_add_f32_dpp v144, v144, v144 quad_perm:[1,0,3,2] row_mask:0xf bank_mask:0xf
	v_add_f32_dpp v145, v145, v145 quad_perm:[1,0,3,2] row_mask:0xf bank_mask:0xf
	v_add_f32_dpp v142, v142, v142 quad_perm:[2,3,0,1] row_mask:0xf bank_mask:0xf
	v_add_f32_dpp v143, v143, v143 quad_perm:[2,3,0,1] row_mask:0xf bank_mask:0xf
	v_add_f32_dpp v144, v144, v144 quad_perm:[2,3,0,1] row_mask:0xf bank_mask:0xf
	v_add_f32_dpp v145, v145, v145 quad_perm:[2,3,0,1] row_mask:0xf bank_mask:0xf
	v_add_f32_dpp v142, v142, v142 row_half_mirror row_mask:0xf bank_mask:0xf
	v_add_f32_dpp v143, v143, v143 row_half_mirror row_mask:0xf bank_mask:0xf
	v_add_f32_dpp v144, v144, v144 row_half_mirror row_mask:0xf bank_mask:0xf
	v_add_f32_dpp v145, v145, v145 row_half_mirror row_mask:0xf bank_mask:0xf
	v_add_f32_dpp v142, v142, v142 row_mirror row_mask:0xf bank_mask:0xf
	v_add_f32_dpp v143, v143, v143 row_mirror row_mask:0xf bank_mask:0xf
	v_add_f32_dpp v144, v144, v144 row_mirror row_mask:0xf bank_mask:0xf
	v_add_f32_dpp v145, v145, v145 row_mirror row_mask:0xf bank_mask:0xf
	s_nop 1
	v_cmp_eq_u32_e32 vcc, 12, v148
	v_cndmask_b32_e32 v147, v147, v142, vcc
	v_cmp_eq_u32_e32 vcc, 13, v148
	v_cndmask_b32_e32 v147, v147, v143, vcc
	v_cmp_eq_u32_e32 vcc, 14, v148
	v_cndmask_b32_e32 v147, v147, v144, vcc
	v_cmp_eq_u32_e32 vcc, 15, v148
	v_cndmask_b32_e32 v147, v147, v145, vcc
	ds_write_b32 v149, v146 offset:256
	ds_write_b32 v149, v147 offset:512
	s_waitcnt lgkmcnt(0)
	ds_read_b32 v23, v22 offset:256
	ds_read_b32 v2, v22 offset:512
	s_waitcnt lgkmcnt(0)
	v_max_f32_e32 v3, v23, v2
	ds_bpermute_b32 v4, v16, v3
	v_add_f32_e32 v77, v20, v21
	v_mov_b32_e32 v45, s15
	v_add_u32_e32 v82, s22, v65
	s_waitcnt lgkmcnt(0)
	v_max_f32_e32 v4, v4, v4
	v_max_f32_e32 v3, v3, v4
	ds_bpermute_b32 v4, v17, v3
	s_waitcnt lgkmcnt(0)
	v_max_f32_e32 v4, v4, v4
	v_max_f32_e32 v3, v3, v4
	ds_bpermute_b32 v4, v18, v3
	s_waitcnt lgkmcnt(0)
	v_max_f32_e32 v4, v4, v4
	v_max_f32_e32 v3, v3, v4
	ds_bpermute_b32 v4, v19, v3
	s_waitcnt lgkmcnt(0)
	v_max_f32_e32 v4, v4, v4
	v_max_f32_e32 v3, v3, v4
	ds_bpermute_b32 v4, v76, v3
	s_waitcnt lgkmcnt(0)
	v_max_f32_e32 v4, v4, v4
	v_max_f32_e32 v3, v3, v4
	ds_bpermute_b32 v4, v75, v3
	s_waitcnt vmcnt(0)
	v_mul_f32_e32 v78, 0x3fb8aa3b, v29
	s_waitcnt lgkmcnt(0)
	v_max_f32_e32 v4, v4, v4
	v_max_f32_e32 v3, v3, v4
	v_max3_f32 v79, v3, v77, v78
	v_sub_f32_e32 v3, v23, v79
	v_sub_f32_e32 v2, v2, v79
	v_exp_f32_e32 v3, v3
	v_exp_f32_e32 v2, v2
	ds_write2st64_b32 v22, v3, v2 offset0:1 offset1:2
	v_add_f32_e32 v4, v3, v2
	ds_bpermute_b32 v5, v16, v4
	v_cndmask_b32_e64 v16, 0, 1, s[4:5]
	v_lshlrev_b32_e32 v16, 6, v16
	v_add_u32_e32 v20, v50, v16
	v_lshl_or_b32 v44, v20, 2, s14
	s_waitcnt lgkmcnt(0)
	v_add_f32_e32 v4, v4, v5
	ds_bpermute_b32 v5, v17, v4
	v_add_u32_e32 v17, v51, v16
	v_add_u32_e32 v21, v52, v16
	v_lshl_add_u64 v[2:3], v[14:15], 0, v[44:45]
	v_lshl_or_b32 v44, v17, 2, s14
	s_waitcnt lgkmcnt(0)
	v_add_f32_e32 v4, v4, v5
	ds_bpermute_b32 v5, v18, v4
	v_add_u32_e32 v23, v53, v16
	v_add_u32_e32 v24, v54, v16
	v_add_u32_e32 v25, v55, v16
	v_add_u32_e32 v26, v56, v16
	s_waitcnt lgkmcnt(0)
	v_add_f32_e32 v4, v4, v5
	ds_bpermute_b32 v5, v19, v4
	v_add_u32_e32 v28, v57, v16
	v_add_u32_e32 v30, v58, v16
	v_add_u32_e32 v19, v59, v16
	v_add_u32_e32 v34, v60, v16
	s_waitcnt lgkmcnt(0)
	v_add_f32_e32 v4, v4, v5
	ds_bpermute_b32 v5, v76, v4
	v_add_u32_e32 v36, v61, v16
	v_add_u32_e32 v38, v62, v16
	v_add_u32_e32 v40, v63, v16
	v_add_u32_e32 v42, v64, v16
	s_waitcnt lgkmcnt(0)
	v_add_f32_e32 v80, v4, v5
	v_lshl_add_u64 v[4:5], v[14:15], 0, v[44:45]
	v_lshl_or_b32 v44, v21, 2, s14
	v_add_u32_e32 v46, v49, v16
	v_lshl_add_u64 v[16:17], v[14:15], 0, v[44:45]
	v_lshl_or_b32 v44, v23, 2, s14
	v_lshl_add_u64 v[20:21], v[14:15], 0, v[44:45]
	v_lshl_or_b32 v44, v24, 2, s14
	v_lshl_add_u64 v[22:23], v[14:15], 0, v[44:45]
	v_lshl_or_b32 v44, v25, 2, s14
	v_lshl_add_u64 v[24:25], v[14:15], 0, v[44:45]
	v_lshl_or_b32 v44, v26, 2, s14
	v_lshl_add_u64 v[26:27], v[14:15], 0, v[44:45]
	v_lshl_or_b32 v44, v28, 2, s14
	v_lshl_add_u64 v[28:29], v[14:15], 0, v[44:45]
	v_lshl_or_b32 v44, v30, 2, s14
	v_lshl_add_u64 v[30:31], v[14:15], 0, v[44:45]
	v_lshl_or_b32 v44, v19, 2, s14
	v_lshl_add_u64 v[32:33], v[14:15], 0, v[44:45]
	v_lshl_or_b32 v44, v34, 2, s14
	v_lshl_add_u64 v[34:35], v[14:15], 0, v[44:45]
	v_lshl_or_b32 v44, v36, 2, s14
	ds_bpermute_b32 v81, v75, v80
	v_lshl_add_u64 v[36:37], v[14:15], 0, v[44:45]
	v_lshl_or_b32 v44, v38, 2, s14
	v_lshl_add_u64 v[38:39], v[14:15], 0, v[44:45]
	v_lshl_or_b32 v44, v40, 2, s14
	s_waitcnt lgkmcnt(0)
	v_lshl_add_u64 v[40:41], v[14:15], 0, v[44:45]
	v_lshl_or_b32 v44, v42, 2, s14
	v_mov_b32_e32 v18, 0
	v_lshl_add_u64 v[42:43], v[14:15], 0, v[44:45]
	v_lshl_or_b32 v44, v46, 2, s14
	v_lshl_add_u64 v[44:45], v[14:15], 0, v[44:45]
	s_mov_b64 s[14:15], 0
	v_mov_b32_e32 v19, v18
	v_mov_b32_e32 v46, v18
	v_mov_b32_e32 v47, v18
.LBB0_307:
	v_lshl_add_u64 v[84:85], v[44:45], 0, s[14:15]
	v_lshl_add_u64 v[88:89], v[42:43], 0, s[14:15]
	v_lshl_add_u64 v[92:93], v[40:41], 0, s[14:15]
	v_lshl_add_u64 v[96:97], v[38:39], 0, s[14:15]
	v_lshl_add_u64 v[100:101], v[36:37], 0, s[14:15]
	v_lshl_add_u64 v[104:105], v[34:35], 0, s[14:15]
	v_lshl_add_u64 v[108:109], v[32:33], 0, s[14:15]
	v_lshl_add_u64 v[112:113], v[30:31], 0, s[14:15]
	v_lshl_add_u64 v[116:117], v[28:29], 0, s[14:15]
	v_lshl_add_u64 v[120:121], v[26:27], 0, s[14:15]
	v_lshl_add_u64 v[124:125], v[24:25], 0, s[14:15]
	v_lshl_add_u64 v[128:129], v[22:23], 0, s[14:15]
	v_lshl_add_u64 v[132:133], v[20:21], 0, s[14:15]
	v_lshl_add_u64 v[136:137], v[16:17], 0, s[14:15]
	v_lshl_add_u64 v[140:141], v[4:5], 0, s[14:15]
	v_lshl_add_u64 v[144:145], v[2:3], 0, s[14:15]
	global_load_dwordx4 v[84:87], v[84:85], off
	s_nop 0
	global_load_dwordx4 v[88:91], v[88:89], off
	s_nop 0
	global_load_dwordx4 v[92:95], v[92:93], off
	s_nop 0
	global_load_dwordx4 v[96:99], v[96:97], off
	s_nop 0
	global_load_dwordx4 v[100:103], v[100:101], off
	s_nop 0
	global_load_dwordx4 v[104:107], v[104:105], off
	s_nop 0
	global_load_dwordx4 v[108:111], v[108:109], off
	s_nop 0
	global_load_dwordx4 v[112:115], v[112:113], off
	s_nop 0
	global_load_dwordx4 v[116:119], v[116:117], off
	s_nop 0
	global_load_dwordx4 v[120:123], v[120:121], off
	s_nop 0
	global_load_dwordx4 v[124:127], v[124:125], off
	s_nop 0
	global_load_dwordx4 v[128:131], v[128:129], off
	s_nop 0
	global_load_dwordx4 v[132:135], v[132:133], off
	s_nop 0
	global_load_dwordx4 v[136:139], v[136:137], off
	s_nop 0
	global_load_dwordx4 v[140:143], v[140:141], off
	s_nop 0
	global_load_dwordx4 v[144:147], v[144:145], off
	ds_read2_b32 v[148:149], v82 offset1:4
	ds_read2_b32 v[150:151], v82 offset0:8 offset1:12
	ds_read2_b32 v[152:153], v82 offset0:16 offset1:20
	ds_read2_b32 v[154:155], v82 offset0:24 offset1:28
	ds_read2_b32 v[156:157], v82 offset0:32 offset1:36
	ds_read2_b32 v[158:159], v82 offset0:40 offset1:44
	ds_read2_b32 v[160:161], v82 offset0:48 offset1:52
	ds_read2_b32 v[162:163], v82 offset0:56 offset1:60
	s_waitcnt lgkmcnt(7)
	v_mov_b32_e32 v164, v149
	s_waitcnt lgkmcnt(6)
	v_mov_b32_e32 v166, v151
	s_waitcnt lgkmcnt(5)
	v_mov_b32_e32 v168, v153
	s_waitcnt lgkmcnt(4)
	v_mov_b32_e32 v170, v155
	s_waitcnt lgkmcnt(3)
	v_mov_b32_e32 v172, v157
	s_waitcnt lgkmcnt(2)
	v_mov_b32_e32 v174, v159
	s_waitcnt lgkmcnt(1)
	v_mov_b32_e32 v176, v161
	s_add_u32 s14, s14, 0x8000
	s_addc_u32 s15, s15, 0
	s_waitcnt lgkmcnt(0)
	v_mov_b32_e32 v178, v163
	v_add_u32_e32 v82, 0x100, v82
	s_cmp_eq_u32 s14, 0x10000
	s_waitcnt vmcnt(15)
	v_pk_fma_f32 v[18:19], v[84:85], v[148:149], v[18:19] op_sel_hi:[1,0,1]
	v_pk_fma_f32 v[46:47], v[86:87], v[148:149], v[46:47] op_sel_hi:[1,0,1]
	s_waitcnt vmcnt(14)
	v_pk_fma_f32 v[18:19], v[88:89], v[164:165], v[18:19] op_sel_hi:[1,0,1]
	v_pk_fma_f32 v[46:47], v[90:91], v[164:165], v[46:47] op_sel_hi:[1,0,1]
	s_waitcnt vmcnt(13)
	v_pk_fma_f32 v[18:19], v[92:93], v[150:151], v[18:19] op_sel_hi:[1,0,1]
	v_pk_fma_f32 v[46:47], v[94:95], v[150:151], v[46:47] op_sel_hi:[1,0,1]
	s_waitcnt vmcnt(12)
	v_pk_fma_f32 v[18:19], v[96:97], v[166:167], v[18:19] op_sel_hi:[1,0,1]
	v_pk_fma_f32 v[46:47], v[98:99], v[166:167], v[46:47] op_sel_hi:[1,0,1]
	s_waitcnt vmcnt(11)
	v_pk_fma_f32 v[18:19], v[100:101], v[152:153], v[18:19] op_sel_hi:[1,0,1]
	v_pk_fma_f32 v[46:47], v[102:103], v[152:153], v[46:47] op_sel_hi:[1,0,1]
	s_waitcnt vmcnt(10)
	v_pk_fma_f32 v[18:19], v[104:105], v[168:169], v[18:19] op_sel_hi:[1,0,1]
	v_pk_fma_f32 v[46:47], v[106:107], v[168:169], v[46:47] op_sel_hi:[1,0,1]
	s_waitcnt vmcnt(9)
	v_pk_fma_f32 v[18:19], v[108:109], v[154:155], v[18:19] op_sel_hi:[1,0,1]
	v_pk_fma_f32 v[46:47], v[110:111], v[154:155], v[46:47] op_sel_hi:[1,0,1]
	s_waitcnt vmcnt(8)
	v_pk_fma_f32 v[18:19], v[112:113], v[170:171], v[18:19] op_sel_hi:[1,0,1]
	v_pk_fma_f32 v[46:47], v[114:115], v[170:171], v[46:47] op_sel_hi:[1,0,1]
	s_waitcnt vmcnt(7)
	v_pk_fma_f32 v[18:19], v[116:117], v[156:157], v[18:19] op_sel_hi:[1,0,1]
	v_pk_fma_f32 v[46:47], v[118:119], v[156:157], v[46:47] op_sel_hi:[1,0,1]
	s_waitcnt vmcnt(6)
	v_pk_fma_f32 v[18:19], v[120:121], v[172:173], v[18:19] op_sel_hi:[1,0,1]
	v_pk_fma_f32 v[46:47], v[122:123], v[172:173], v[46:47] op_sel_hi:[1,0,1]
	s_waitcnt vmcnt(5)
	v_pk_fma_f32 v[18:19], v[124:125], v[158:159], v[18:19] op_sel_hi:[1,0,1]
	v_pk_fma_f32 v[46:47], v[126:127], v[158:159], v[46:47] op_sel_hi:[1,0,1]
	s_waitcnt vmcnt(4)
	v_pk_fma_f32 v[18:19], v[128:129], v[174:175], v[18:19] op_sel_hi:[1,0,1]
	v_pk_fma_f32 v[46:47], v[130:131], v[174:175], v[46:47] op_sel_hi:[1,0,1]
	s_waitcnt vmcnt(3)
	v_pk_fma_f32 v[18:19], v[132:133], v[160:161], v[18:19] op_sel_hi:[1,0,1]
	v_pk_fma_f32 v[46:47], v[134:135], v[160:161], v[46:47] op_sel_hi:[1,0,1]
	s_waitcnt vmcnt(2)
	v_pk_fma_f32 v[18:19], v[136:137], v[176:177], v[18:19] op_sel_hi:[1,0,1]
	v_pk_fma_f32 v[46:47], v[138:139], v[176:177], v[46:47] op_sel_hi:[1,0,1]
	s_waitcnt vmcnt(1)
	v_pk_fma_f32 v[18:19], v[140:141], v[162:163], v[18:19] op_sel_hi:[1,0,1]
	v_pk_fma_f32 v[46:47], v[142:143], v[162:163], v[46:47] op_sel_hi:[1,0,1]
	s_waitcnt vmcnt(0)
	v_pk_fma_f32 v[18:19], v[144:145], v[178:179], v[18:19] op_sel_hi:[1,0,1]
	v_pk_fma_f32 v[46:47], v[146:147], v[178:179], v[46:47] op_sel_hi:[1,0,1]
	s_cbranch_scc0 .LBB0_307
	ds_bpermute_b32 v2, v76, v18
	ds_bpermute_b32 v3, v76, v19
	ds_bpermute_b32 v16, v76, v46
	ds_bpermute_b32 v17, v76, v47
	s_waitcnt lgkmcnt(2)
	v_pk_add_f32 v[2:3], v[18:19], v[2:3]
	ds_bpermute_b32 v4, v75, v2
	s_waitcnt lgkmcnt(1)
	v_pk_add_f32 v[16:17], v[46:47], v[16:17]
	ds_bpermute_b32 v5, v75, v3
	ds_bpermute_b32 v18, v75, v16
	ds_bpermute_b32 v19, v75, v17
	s_and_saveexec_b64 s[14:15], s[0:1]
	s_cbranch_execz .LBB0_301
	v_sub_f32_e32 v24, v77, v79
	v_sub_f32_e32 v22, v78, v79
	s_waitcnt lgkmcnt(0)
	v_pk_add_f32 v[16:17], v[16:17], v[18:19]
	v_exp_f32_e32 v18, v24
	v_exp_f32_e32 v19, v22
	v_add_f32_e32 v23, v80, v81
	s_lshl_b64 s[8:9], s[8:9], 11
	s_add_u32 s8, s76, s8
	v_add_f32_e32 v22, v18, v23
	s_addc_u32 s9, s77, s9
	s_lshl_b32 s12, s19, 1
	v_add_f32_e32 v19, v19, v22
	s_add_u32 s8, s8, s12
	v_div_scale_f32 v22, s[12:13], v19, v19, 1.0
	v_rcp_f32_e32 v23, v22
	v_div_scale_f32 v24, vcc, 1.0, v19, 1.0
	v_pk_add_f32 v[2:3], v[2:3], v[4:5]
	v_fma_f32 v25, -v22, v23, 1.0
	v_fmac_f32_e32 v23, v25, v23
	v_mul_f32_e32 v25, v24, v23
	v_fma_f32 v26, -v22, v25, v24
	v_fmac_f32_e32 v25, v26, v23
	v_lshlrev_b32_e32 v4, 1, v12
	v_mov_b32_e32 v5, v7
	s_addc_u32 s9, s9, 0
	v_fma_f32 v22, -v22, v25, v24
	v_lshl_add_u64 v[4:5], s[8:9], 0, v[4:5]
	v_div_fmas_f32 v22, v22, v23, v25
	v_add_co_u32_e32 v4, vcc, 0x4100000, v4
	v_div_fixup_f32 v22, v22, v19, 1.0
	s_nop 0
	v_addc_co_u32_e32 v5, vcc, 0, v5, vcc
	s_waitcnt vmcnt(0)
	v_and_b32_e32 v25, 0xffff0000, v181
	v_lshlrev_b32_e32 v24, 16, v181
	v_and_b32_e32 v21, 0xffff0000, v180
	v_lshlrev_b32_e32 v20, 16, v180
	v_pk_fma_f32 v[2:3], v[18:19], v[20:21], v[2:3] op_sel_hi:[0,1,1]
	v_pk_fma_f32 v[16:17], v[18:19], v[24:25], v[16:17] op_sel_hi:[0,1,1]
	v_pk_mul_f32 v[2:3], v[22:23], v[2:3] op_sel_hi:[0,1]
	v_pk_mul_f32 v[16:17], v[22:23], v[16:17] op_sel_hi:[0,1]
	v_cvt_pk_bf16_f32 v2, v2, v3
	v_cvt_pk_bf16_f32 v3, v16, v17
	global_store_dwordx2 v[4:5], v[2:3], off offset:1024
	s_branch .LBB0_301
